# same as previous plus page-friendly 4kb x 11nb block mapping for the w_up transposes
# speedup vs baseline: 1.0393x; 1.0038x over previous
; template <int MODE>
; __device__ __forceinline__ void transpose_item(const float* W, int N, bf16_t* WT, int ldt, int coff, LAS float* scr, int item, int lane, const float* g) {
;     const int nblk = N / 32, kb = item / nblk, nb = item % nblk, k0 = 64 * kb, n0 = 32 * nb;
; #pragma unroll 8
;     for (int i = 0; i < 32; ++i) { const int kk = 2 * i + (lane >> 5); float v = W[(size_t)(k0 + kk) * N + n0 + (lane & 31)]; if (MODE >= 1) v *= g[k0 + kk]; scr[kk * 33 + (lane & 31)] = v; }
; __global__ void __launch_bounds__(512, 2) mk_fwd(Args a) {
;     ...
;         constexpr int I_U = 32 * 352, I_D = 88 * 64;
;         for (int it = gw; it < I_U + I_D; it += NGW) {
;             if (it < I_U) transpose_item<1>(a.in[I_WUP], 2 * DFF, WUP, DM, 0, scr, it, lane, a.in[I_N2]);
;             else transpose_item<0>(a.in[I_WDN], DM, WDN, DFF, 0, scr, it - I_U, lane, nullptr);
;         }
;         __syncthreads();
;         pg8::Gemm g{OOB, WAB, DM, DM, 1024}; pg8::StaticOrder S; S.init(MTOT / 256, DM / 256, G, bx, QLIM);
.LBB0_642:
	s_cmp_lt_i32 s70, 4
	s_cselect_b64 s[4:5], -1, 0
	s_add_u32 s44, s68, 0x1af00000
	s_addc_u32 s45, s69, 0
	s_add_u32 s6, s68, 0x1db00000
	s_addc_u32 s7, s69, 0
	v_writelane_b32 v250, s6, 20
	s_cmpk_lg_i32 s3, 0x100
	s_movk_i32 s8, 0x200
	v_writelane_b32 v250, s7, 21
	s_cselect_b64 s[6:7], -1, 0
	v_writelane_b32 v250, s6, 26
	s_cmpk_eq_i32 s3, 0x100
	s_nop 0
	v_writelane_b32 v250, s7, 27
	s_cselect_b64 s[6:7], -1, 0
	v_writelane_b32 v250, s6, 24
	s_nop 1
	v_writelane_b32 v250, s7, 25
	s_and_b64 s[6:7], s[6:7], exec
	s_cselect_b32 s88, s8, 0x7fffffff
	s_and_b64 s[4:5], s[4:5], s[0:1]
	s_andn2_b64 vcc, exec, s[4:5]
	s_cbranch_vccnz .LBB0_712
	s_cmpk_lt_i32 s96, 0x400
	s_cbranch_scc1 .LBB0_670
	s_and_b32 s0, s96, 7
	s_lshl_b32 s0, s0, 14
	s_and_b32 s1, s96, 7
	s_lshl_b32 s1, s1, 7
	s_add_u32 s1, s1, s2
	s_sub_u32 s1, s1, 0x80
	s_cmp_lt_u32 s1, 0x1600
	s_cbranch_scc0 .Ltr_done_p3up
	v_lshrrev_b32_e32 v168, 3, v220
	v_and_b32_e32 v169, 7, v220
	v_mul_u32_u24_e32 v170, 0xb000, v168
	v_lshl_add_u32 v171, v169, 4, v170
	v_add_u32_e32 v172, 0x58000, v171
	v_add_u32_e32 v173, 0xb0000, v171
	v_add_u32_e32 v174, 0x108000, v171
	v_add_u32_e32 v175, 0x160000, v171
	v_add_u32_e32 v177, 0x1b8000, v171
	v_add_u32_e32 v182, 0x210000, v171
	v_add_u32_e32 v183, 0x268000, v171
	v_mul_u32_u24_e32 v170, 0x84, v168
	v_lshl_add_u32 v170, v169, 4, v170
	v_add_u32_e32 v189, s0, v170
	v_mul_u32_u24_e32 v170, 0x420, v169
	v_lshl_add_u32 v170, v168, 2, v170
	v_add_u32_e32 v190, s0, v170
	v_mul_u32_u24_e32 v170, 0x1000, v168
	v_lshl_add_u32 v184, v169, 4, v170
	v_add_u32_e32 v185, 0x8000, v184
	v_add_u32_e32 v186, 0x10000, v184
	v_add_u32_e32 v188, 0x18000, v184
	v_lshlrev_b32_e32 v191, 5, v169
	s_mov_b32 s7, s1
	s_mov_b32 s6, s1
	s_lshr_b32 s34, s6, 7
	s_mul_hi_u32 s40, s34, 0xba2e8ba3
	s_lshr_b32 s40, s40, 3
	s_mul_i32 s41, s40, 11
	s_sub_u32 s34, s34, s41
	s_and_b32 s9, s6, 127
	s_and_b32 s41, s9, 31
	s_mul_i32 s41, s41, 11
	s_add_u32 s34, s34, s41
	s_lshr_b32 s9, s9, 5
	s_lshl_b32 s9, s9, 2
	s_add_u32 s9, s9, s40
	s_mul_i32 s35, s9, 0x2c0000
	s_lshl_b32 s34, s34, 7
	s_add_u32 s35, s35, s34
	s_add_u32 s10, s22, s35
	s_addc_u32 s11, s23, 0
	global_load_dwordx4 v[0:3], v171, s[10:11]
	global_load_dwordx4 v[4:7], v172, s[10:11]
	global_load_dwordx4 v[8:11], v173, s[10:11]
	global_load_dwordx4 v[12:15], v174, s[10:11]
	global_load_dwordx4 v[16:19], v175, s[10:11]
	global_load_dwordx4 v[20:23], v177, s[10:11]
	global_load_dwordx4 v[24:27], v182, s[10:11]
	global_load_dwordx4 v[28:31], v183, s[10:11]
	s_lshl_b32 s35, s9, 8
	s_add_u32 s32, s20, s35
	s_addc_u32 s33, s21, 0
	global_load_dwordx4 v[144:147], v191, s[32:33]
	global_load_dwordx4 v[148:151], v191, s[32:33] offset:16
	s_add_u32 s6, s6, 0x400
	s_cmp_lt_u32 s6, 0x1600
	s_cbranch_scc0 .Ltr_p1_p3up
	s_lshr_b32 s34, s6, 7
	s_mul_hi_u32 s40, s34, 0xba2e8ba3
	s_lshr_b32 s40, s40, 3
	s_mul_i32 s41, s40, 11
	s_sub_u32 s34, s34, s41
	s_and_b32 s9, s6, 127
	s_and_b32 s41, s9, 31
	s_mul_i32 s41, s41, 11
	s_add_u32 s34, s34, s41
	s_lshr_b32 s9, s9, 5
	s_lshl_b32 s9, s9, 2
	s_add_u32 s9, s9, s40
	s_mul_i32 s35, s9, 0x2c0000
	s_lshl_b32 s34, s34, 7
	s_add_u32 s35, s35, s34
	s_add_u32 s10, s22, s35
	s_addc_u32 s11, s23, 0
	global_load_dwordx4 v[32:35], v171, s[10:11]
	global_load_dwordx4 v[36:39], v172, s[10:11]
	global_load_dwordx4 v[40:43], v173, s[10:11]
	global_load_dwordx4 v[44:47], v174, s[10:11]
	global_load_dwordx4 v[48:51], v175, s[10:11]
	global_load_dwordx4 v[52:55], v177, s[10:11]
	global_load_dwordx4 v[56:59], v182, s[10:11]
	global_load_dwordx4 v[60:63], v183, s[10:11]
	s_lshl_b32 s35, s9, 8
	s_add_u32 s32, s20, s35
	s_addc_u32 s33, s21, 0
	global_load_dwordx4 v[152:155], v191, s[32:33]
	global_load_dwordx4 v[156:159], v191, s[32:33] offset:16

; template <int MODE>
; __device__ __forceinline__ void transpose_item(const float* W, int N, bf16_t* WT, int ldt, int coff, LAS float* scr, int item, int lane, const float* g) {
;     const int nblk = N / 32, kb = item / nblk, nb = item % nblk, k0 = 64 * kb, n0 = 32 * nb;
; #pragma unroll 8
;     for (int i = 0; i < 32; ++i) { const int kk = 2 * i + (lane >> 5); float v = W[(size_t)(k0 + kk) * N + n0 + (lane & 31)]; if (MODE >= 1) v *= g[k0 + kk]; scr[kk * 33 + (lane & 31)] = v; }
.Ltr_st0_p3up:
	s_cmp_lt_u32 s6, 0x1600
	s_cbranch_scc0 .Ltr_nl0_p3up
	s_lshr_b32 s34, s6, 7
	s_mul_hi_u32 s40, s34, 0xba2e8ba3
	s_lshr_b32 s40, s40, 3
	s_mul_i32 s41, s40, 11
	s_sub_u32 s34, s34, s41
	s_and_b32 s9, s6, 127
	s_and_b32 s41, s9, 31
	s_mul_i32 s41, s41, 11
	s_add_u32 s34, s34, s41
	s_lshr_b32 s9, s9, 5
	s_lshl_b32 s9, s9, 2
	s_add_u32 s9, s9, s40
	s_mul_i32 s35, s9, 0x2c0000
	s_lshl_b32 s34, s34, 7
	s_add_u32 s35, s35, s34
	s_add_u32 s10, s22, s35
	s_addc_u32 s11, s23, 0
	global_load_dwordx4 v[64:67], v171, s[10:11]
	global_load_dwordx4 v[68:71], v172, s[10:11]
	global_load_dwordx4 v[72:75], v173, s[10:11]
	global_load_dwordx4 v[76:79], v174, s[10:11]
	global_load_dwordx4 v[80:83], v175, s[10:11]
	global_load_dwordx4 v[84:87], v177, s[10:11]
	global_load_dwordx4 v[88:91], v182, s[10:11]
	global_load_dwordx4 v[92:95], v183, s[10:11]
	s_lshl_b32 s35, s9, 8
	s_add_u32 s32, s20, s35
	s_addc_u32 s33, s21, 0
	global_load_dwordx4 v[160:163], v191, s[32:33]
	global_load_dwordx4 v[164:167], v191, s[32:33] offset:16
	s_waitcnt vmcnt(20)
	s_branch .Ltr_pr0_p3up

; #define LAS __attribute__((address_space(3)))
; __device__ __forceinline__ unsigned cvtpk(float lo, float hi) { f32x2_t v = {lo, hi}; bf16x2_t b = __builtin_convertvector(v, bf16x2_t); return __builtin_bit_cast(unsigned, b); }
; template <int MODE>
; __device__ __forceinline__ void transpose_item(const float* W, int N, bf16_t* WT, int ldt, int coff, LAS float* scr, int item, int lane, const float* g) {
;     const int nblk = N / 32, kb = item / nblk, nb = item % nblk, k0 = 64 * kb, n0 = 32 * nb;
; #pragma unroll 8
;     for (int i = 0; i < 32; ++i) { const int kk = 2 * i + (lane >> 5); float v = W[(size_t)(k0 + kk) * N + n0 + (lane & 31)]; if (MODE >= 1) v *= g[k0 + kk]; scr[kk * 33 + (lane & 31)] = v; }
;     asm volatile("s_waitcnt lgkmcnt(0)" ::: "memory");
;     const int c = lane & 7;
; #pragma unroll
;     for (int j = 0; j < 4; ++j) {
;         const int n = (lane >> 3) + 8 * j; const LAS float* s = scr + (8 * c) * 33 + n;
;         u32x4 o; o.x = cvtpk(s[0 * 33], s[1 * 33]); o.y = cvtpk(s[2 * 33], s[3 * 33]); o.z = cvtpk(s[4 * 33], s[5 * 33]); o.w = cvtpk(s[6 * 33], s[7 * 33]);
;         int dr = n0 + n;
;         if (MODE == 1) { dr = (dr < DFF) ? 256 * (dr >> 7) + (dr & 127) : 256 * ((dr - DFF) >> 7) + 128 + ((dr - DFF) & 127); }
;         if (MODE == 2) {
;             if (dr >= 6144) { const int t = dr - 6144, ch = t & 2047; dr = 6144 + 256 * (ch >> 7) + ((t >> 11) << 7) + (ch & 127); }
;             else if (dr >= 4096) { const int t = dr - 4096, ch = t & 1023; dr = 4096 + 256 * (ch >> 7) + ((t >> 10) << 7) + (ch & 127); }
;         }
;         *(u32x4*)(WT + (size_t)dr * ldt + coff + k0 + 8 * c) = o;
.Ltr_pr0_p3up:
	s_add_u32 s6, s6, 0x400
	s_lshr_b32 s34, s7, 7
	s_mul_hi_u32 s40, s34, 0xba2e8ba3
	s_lshr_b32 s40, s40, 3
	s_mul_i32 s41, s40, 11
	s_sub_u32 s34, s34, s41
	s_and_b32 s9, s7, 127
	s_and_b32 s41, s9, 31
	s_mul_i32 s41, s41, 11
	s_add_u32 s34, s34, s41
	s_lshr_b32 s9, s9, 5
	s_lshl_b32 s9, s9, 2
	s_add_u32 s9, s9, s40
	s_cmp_ge_u32 s34, 0xb0
	s_cselect_b32 s35, 0xb0, 0
	s_cselect_b32 s36, 0x80, 0
	s_sub_u32 s34, s34, s35
	s_lshl_b32 s34, s34, 5
	s_and_b32 s35, s34, 0xffffff80
	s_and_b32 s34, s34, 0x7f
	s_lshl_b32 s35, s35, 1
	s_add_u32 s35, s35, s34
	s_add_u32 s35, s35, s36
	s_mul_i32 s35, s35, 0x1000
	s_lshl_b32 s9, s9, 7
	s_add_u32 s35, s35, s9
	s_add_u32 s14, s44, s35
	s_addc_u32 s15, s45, 0
	ds_write_b32 v189, v0 offset:0
	ds_write_b32 v189, v1 offset:4
	ds_write_b32 v189, v2 offset:8
	ds_write_b32 v189, v3 offset:12
	ds_write_b32 v189, v4 offset:1056
	ds_write_b32 v189, v5 offset:1060
	ds_write_b32 v189, v6 offset:1064
	ds_write_b32 v189, v7 offset:1068
	ds_write_b32 v189, v8 offset:2112
	ds_write_b32 v189, v9 offset:2116
	ds_write_b32 v189, v10 offset:2120
	ds_write_b32 v189, v11 offset:2124
	ds_write_b32 v189, v12 offset:3168
	ds_write_b32 v189, v13 offset:3172
	ds_write_b32 v189, v14 offset:3176
	ds_write_b32 v189, v15 offset:3180
	ds_write_b32 v189, v16 offset:4224
	ds_write_b32 v189, v17 offset:4228
	ds_write_b32 v189, v18 offset:4232
	ds_write_b32 v189, v19 offset:4236
	ds_write_b32 v189, v20 offset:5280
	ds_write_b32 v189, v21 offset:5284
	ds_write_b32 v189, v22 offset:5288
	ds_write_b32 v189, v23 offset:5292
	ds_write_b32 v189, v24 offset:6336
	ds_write_b32 v189, v25 offset:6340
	ds_write_b32 v189, v26 offset:6344
	ds_write_b32 v189, v27 offset:6348
	ds_write_b32 v189, v28 offset:7392
	ds_write_b32 v189, v29 offset:7396
	ds_write_b32 v189, v30 offset:7400
	ds_write_b32 v189, v31 offset:7404
	s_waitcnt lgkmcnt(0)
	ds_read2_b32 v[96:97], v190 offset0:0 offset1:8
	ds_read2_b32 v[100:101], v190 offset0:33 offset1:41
	ds_read2_b32 v[104:105], v190 offset0:66 offset1:74
	ds_read2_b32 v[108:109], v190 offset0:99 offset1:107
	ds_read2_b32 v[112:113], v190 offset0:132 offset1:140
	ds_read2_b32 v[116:117], v190 offset0:165 offset1:173
	ds_read2_b32 v[120:121], v190 offset0:198 offset1:206
	ds_read2_b32 v[124:125], v190 offset0:231 offset1:239
	ds_read2_b32 v[98:99], v190 offset0:16 offset1:24
	ds_read2_b32 v[102:103], v190 offset0:49 offset1:57
	ds_read2_b32 v[106:107], v190 offset0:82 offset1:90
	ds_read2_b32 v[110:111], v190 offset0:115 offset1:123
	ds_read2_b32 v[114:115], v190 offset0:148 offset1:156
	ds_read2_b32 v[118:119], v190 offset0:181 offset1:189
	ds_read2_b32 v[122:123], v190 offset0:214 offset1:222
	ds_read2_b32 v[126:127], v190 offset0:247 offset1:255
	s_waitcnt lgkmcnt(0)
	v_mul_f32_e32 v96, v144, v96
	v_mul_f32_e32 v97, v144, v97
	v_mul_f32_e32 v98, v144, v98
	v_mul_f32_e32 v99, v144, v99
	v_mul_f32_e32 v100, v145, v100
	v_mul_f32_e32 v101, v145, v101
	v_mul_f32_e32 v102, v145, v102
	v_mul_f32_e32 v103, v145, v103
	v_mul_f32_e32 v104, v146, v104
	v_mul_f32_e32 v105, v146, v105
	v_mul_f32_e32 v106, v146, v106
	v_mul_f32_e32 v107, v146, v107
	v_mul_f32_e32 v108, v147, v108
	v_mul_f32_e32 v109, v147, v109
	v_mul_f32_e32 v110, v147, v110
	v_mul_f32_e32 v111, v147, v111
	v_mul_f32_e32 v112, v148, v112
	v_mul_f32_e32 v113, v148, v113
	v_mul_f32_e32 v114, v148, v114
	v_mul_f32_e32 v115, v148, v115
	v_mul_f32_e32 v116, v149, v116
	v_mul_f32_e32 v117, v149, v117
	v_mul_f32_e32 v118, v149, v118
	v_mul_f32_e32 v119, v149, v119
	v_mul_f32_e32 v120, v150, v120
	v_mul_f32_e32 v121, v150, v121
	v_mul_f32_e32 v122, v150, v122
	v_mul_f32_e32 v123, v150, v123
	v_mul_f32_e32 v124, v151, v124
	v_mul_f32_e32 v125, v151, v125
	v_mul_f32_e32 v126, v151, v126
	v_mul_f32_e32 v127, v151, v127
	v_cvt_pk_bf16_f32 v128, v96, v100
	v_cvt_pk_bf16_f32 v129, v104, v108
	v_cvt_pk_bf16_f32 v130, v112, v116
	v_cvt_pk_bf16_f32 v131, v120, v124
	global_store_dwordx4 v184, v[128:131], s[14:15]
	v_cvt_pk_bf16_f32 v132, v97, v101
	v_cvt_pk_bf16_f32 v133, v105, v109
	v_cvt_pk_bf16_f32 v134, v113, v117
	v_cvt_pk_bf16_f32 v135, v121, v125
	global_store_dwordx4 v185, v[132:135], s[14:15]
	v_cvt_pk_bf16_f32 v136, v98, v102
	v_cvt_pk_bf16_f32 v137, v106, v110
	v_cvt_pk_bf16_f32 v138, v114, v118
	v_cvt_pk_bf16_f32 v139, v122, v126
	global_store_dwordx4 v186, v[136:139], s[14:15]
	v_cvt_pk_bf16_f32 v140, v99, v103
	v_cvt_pk_bf16_f32 v141, v107, v111
	v_cvt_pk_bf16_f32 v142, v115, v119
	v_cvt_pk_bf16_f32 v143, v123, v127
	global_store_dwordx4 v188, v[140:143], s[14:15]
	s_add_u32 s7, s7, 0x400
	s_cmp_lt_u32 s7, 0x1600
	s_cbranch_scc0 .Ltr_done_p3up
.Ltr_st1_p3up:
	s_cmp_lt_u32 s6, 0x1600
	s_cbranch_scc0 .Ltr_nl1_p3up
	s_lshr_b32 s34, s6, 7
	s_mul_hi_u32 s40, s34, 0xba2e8ba3
	s_lshr_b32 s40, s40, 3
	s_mul_i32 s41, s40, 11
	s_sub_u32 s34, s34, s41
	s_and_b32 s9, s6, 127
	s_and_b32 s41, s9, 31
	s_mul_i32 s41, s41, 11
	s_add_u32 s34, s34, s41
	s_lshr_b32 s9, s9, 5
	s_lshl_b32 s9, s9, 2
	s_add_u32 s9, s9, s40
	s_mul_i32 s35, s9, 0x2c0000
	s_lshl_b32 s34, s34, 7
	s_add_u32 s35, s35, s34
	s_add_u32 s10, s22, s35
	s_addc_u32 s11, s23, 0
	global_load_dwordx4 v[0:3], v171, s[10:11]
	global_load_dwordx4 v[4:7], v172, s[10:11]
	global_load_dwordx4 v[8:11], v173, s[10:11]
	global_load_dwordx4 v[12:15], v174, s[10:11]
	global_load_dwordx4 v[16:19], v175, s[10:11]
	global_load_dwordx4 v[20:23], v177, s[10:11]
	global_load_dwordx4 v[24:27], v182, s[10:11]
	global_load_dwordx4 v[28:31], v183, s[10:11]
	s_lshl_b32 s35, s9, 8
	s_add_u32 s32, s20, s35
	s_addc_u32 s33, s21, 0
	global_load_dwordx4 v[144:147], v191, s[32:33]
	global_load_dwordx4 v[148:151], v191, s[32:33] offset:16
	s_waitcnt vmcnt(20)
	s_branch .Ltr_pr1_p3up

; #define LAS __attribute__((address_space(3)))
; __device__ __forceinline__ unsigned cvtpk(float lo, float hi) { f32x2_t v = {lo, hi}; bf16x2_t b = __builtin_convertvector(v, bf16x2_t); return __builtin_bit_cast(unsigned, b); }
; template <int MODE>
; __device__ __forceinline__ void transpose_item(const float* W, int N, bf16_t* WT, int ldt, int coff, LAS float* scr, int item, int lane, const float* g) {
;     const int nblk = N / 32, kb = item / nblk, nb = item % nblk, k0 = 64 * kb, n0 = 32 * nb;
; #pragma unroll 8
;     for (int i = 0; i < 32; ++i) { const int kk = 2 * i + (lane >> 5); float v = W[(size_t)(k0 + kk) * N + n0 + (lane & 31)]; if (MODE >= 1) v *= g[k0 + kk]; scr[kk * 33 + (lane & 31)] = v; }
;     asm volatile("s_waitcnt lgkmcnt(0)" ::: "memory");
;     const int c = lane & 7;
; #pragma unroll
;     for (int j = 0; j < 4; ++j) {
;         const int n = (lane >> 3) + 8 * j; const LAS float* s = scr + (8 * c) * 33 + n;
;         u32x4 o; o.x = cvtpk(s[0 * 33], s[1 * 33]); o.y = cvtpk(s[2 * 33], s[3 * 33]); o.z = cvtpk(s[4 * 33], s[5 * 33]); o.w = cvtpk(s[6 * 33], s[7 * 33]);
;         int dr = n0 + n;
;         if (MODE == 1) { dr = (dr < DFF) ? 256 * (dr >> 7) + (dr & 127) : 256 * ((dr - DFF) >> 7) + 128 + ((dr - DFF) & 127); }
;         if (MODE == 2) {
;             if (dr >= 6144) { const int t = dr - 6144, ch = t & 2047; dr = 6144 + 256 * (ch >> 7) + ((t >> 11) << 7) + (ch & 127); }
;             else if (dr >= 4096) { const int t = dr - 4096, ch = t & 1023; dr = 4096 + 256 * (ch >> 7) + ((t >> 10) << 7) + (ch & 127); }
;         }
;         *(u32x4*)(WT + (size_t)dr * ldt + coff + k0 + 8 * c) = o;
.Ltr_pr1_p3up:
	s_add_u32 s6, s6, 0x400
	s_lshr_b32 s34, s7, 7
	s_mul_hi_u32 s40, s34, 0xba2e8ba3
	s_lshr_b32 s40, s40, 3
	s_mul_i32 s41, s40, 11
	s_sub_u32 s34, s34, s41
	s_and_b32 s9, s7, 127
	s_and_b32 s41, s9, 31
	s_mul_i32 s41, s41, 11
	s_add_u32 s34, s34, s41
	s_lshr_b32 s9, s9, 5
	s_lshl_b32 s9, s9, 2
	s_add_u32 s9, s9, s40
	s_cmp_ge_u32 s34, 0xb0
	s_cselect_b32 s35, 0xb0, 0
	s_cselect_b32 s36, 0x80, 0
	s_sub_u32 s34, s34, s35
	s_lshl_b32 s34, s34, 5
	s_and_b32 s35, s34, 0xffffff80
	s_and_b32 s34, s34, 0x7f
	s_lshl_b32 s35, s35, 1
	s_add_u32 s35, s35, s34
	s_add_u32 s35, s35, s36
	s_mul_i32 s35, s35, 0x1000
	s_lshl_b32 s9, s9, 7
	s_add_u32 s35, s35, s9
	s_add_u32 s14, s44, s35
	s_addc_u32 s15, s45, 0
	ds_write_b32 v189, v32 offset:0
	ds_write_b32 v189, v33 offset:4
	ds_write_b32 v189, v34 offset:8
	ds_write_b32 v189, v35 offset:12
	ds_write_b32 v189, v36 offset:1056
	ds_write_b32 v189, v37 offset:1060
	ds_write_b32 v189, v38 offset:1064
	ds_write_b32 v189, v39 offset:1068
	ds_write_b32 v189, v40 offset:2112
	ds_write_b32 v189, v41 offset:2116
	ds_write_b32 v189, v42 offset:2120
	ds_write_b32 v189, v43 offset:2124
	ds_write_b32 v189, v44 offset:3168
	ds_write_b32 v189, v45 offset:3172
	ds_write_b32 v189, v46 offset:3176
	ds_write_b32 v189, v47 offset:3180
	ds_write_b32 v189, v48 offset:4224
	ds_write_b32 v189, v49 offset:4228
	ds_write_b32 v189, v50 offset:4232
	ds_write_b32 v189, v51 offset:4236
	ds_write_b32 v189, v52 offset:5280
	ds_write_b32 v189, v53 offset:5284
	ds_write_b32 v189, v54 offset:5288
	ds_write_b32 v189, v55 offset:5292
	ds_write_b32 v189, v56 offset:6336
	ds_write_b32 v189, v57 offset:6340
	ds_write_b32 v189, v58 offset:6344
	ds_write_b32 v189, v59 offset:6348
	ds_write_b32 v189, v60 offset:7392
	ds_write_b32 v189, v61 offset:7396
	ds_write_b32 v189, v62 offset:7400
	ds_write_b32 v189, v63 offset:7404
	s_waitcnt lgkmcnt(0)
	ds_read2_b32 v[96:97], v190 offset0:0 offset1:8
	ds_read2_b32 v[100:101], v190 offset0:33 offset1:41
	ds_read2_b32 v[104:105], v190 offset0:66 offset1:74
	ds_read2_b32 v[108:109], v190 offset0:99 offset1:107
	ds_read2_b32 v[112:113], v190 offset0:132 offset1:140
	ds_read2_b32 v[116:117], v190 offset0:165 offset1:173
	ds_read2_b32 v[120:121], v190 offset0:198 offset1:206
	ds_read2_b32 v[124:125], v190 offset0:231 offset1:239
	ds_read2_b32 v[98:99], v190 offset0:16 offset1:24
	ds_read2_b32 v[102:103], v190 offset0:49 offset1:57
	ds_read2_b32 v[106:107], v190 offset0:82 offset1:90
	ds_read2_b32 v[110:111], v190 offset0:115 offset1:123
	ds_read2_b32 v[114:115], v190 offset0:148 offset1:156
	ds_read2_b32 v[118:119], v190 offset0:181 offset1:189
	ds_read2_b32 v[122:123], v190 offset0:214 offset1:222
	ds_read2_b32 v[126:127], v190 offset0:247 offset1:255
	s_waitcnt lgkmcnt(0)
	v_mul_f32_e32 v96, v152, v96
	v_mul_f32_e32 v97, v152, v97
	v_mul_f32_e32 v98, v152, v98
	v_mul_f32_e32 v99, v152, v99
	v_mul_f32_e32 v100, v153, v100
	v_mul_f32_e32 v101, v153, v101
	v_mul_f32_e32 v102, v153, v102
	v_mul_f32_e32 v103, v153, v103
	v_mul_f32_e32 v104, v154, v104
	v_mul_f32_e32 v105, v154, v105
	v_mul_f32_e32 v106, v154, v106
	v_mul_f32_e32 v107, v154, v107
	v_mul_f32_e32 v108, v155, v108
	v_mul_f32_e32 v109, v155, v109
	v_mul_f32_e32 v110, v155, v110
	v_mul_f32_e32 v111, v155, v111
	v_mul_f32_e32 v112, v156, v112
	v_mul_f32_e32 v113, v156, v113
	v_mul_f32_e32 v114, v156, v114
	v_mul_f32_e32 v115, v156, v115
	v_mul_f32_e32 v116, v157, v116
	v_mul_f32_e32 v117, v157, v117
	v_mul_f32_e32 v118, v157, v118
	v_mul_f32_e32 v119, v157, v119
	v_mul_f32_e32 v120, v158, v120
	v_mul_f32_e32 v121, v158, v121
	v_mul_f32_e32 v122, v158, v122
	v_mul_f32_e32 v123, v158, v123
	v_mul_f32_e32 v124, v159, v124
	v_mul_f32_e32 v125, v159, v125
	v_mul_f32_e32 v126, v159, v126
	v_mul_f32_e32 v127, v159, v127
	v_cvt_pk_bf16_f32 v128, v96, v100
	v_cvt_pk_bf16_f32 v129, v104, v108
	v_cvt_pk_bf16_f32 v130, v112, v116
	v_cvt_pk_bf16_f32 v131, v120, v124
	global_store_dwordx4 v184, v[128:131], s[14:15]
	v_cvt_pk_bf16_f32 v132, v97, v101
	v_cvt_pk_bf16_f32 v133, v105, v109
	v_cvt_pk_bf16_f32 v134, v113, v117
	v_cvt_pk_bf16_f32 v135, v121, v125
	global_store_dwordx4 v185, v[132:135], s[14:15]
	v_cvt_pk_bf16_f32 v136, v98, v102
	v_cvt_pk_bf16_f32 v137, v106, v110
	v_cvt_pk_bf16_f32 v138, v114, v118
	v_cvt_pk_bf16_f32 v139, v122, v126
	global_store_dwordx4 v186, v[136:139], s[14:15]
	v_cvt_pk_bf16_f32 v140, v99, v103
	v_cvt_pk_bf16_f32 v141, v107, v111
	v_cvt_pk_bf16_f32 v142, v115, v119
	v_cvt_pk_bf16_f32 v143, v123, v127
	global_store_dwordx4 v188, v[140:143], s[14:15]
	s_add_u32 s7, s7, 0x400
	s_cmp_lt_u32 s7, 0x1600
	s_cbranch_scc0 .Ltr_done_p3up
.Ltr_st2_p3up:
	s_cmp_lt_u32 s6, 0x1600
	s_cbranch_scc0 .Ltr_nl2_p3up
	s_lshr_b32 s34, s6, 7
	s_mul_hi_u32 s40, s34, 0xba2e8ba3
	s_lshr_b32 s40, s40, 3
	s_mul_i32 s41, s40, 11
	s_sub_u32 s34, s34, s41
	s_and_b32 s9, s6, 127
	s_and_b32 s41, s9, 31
	s_mul_i32 s41, s41, 11
	s_add_u32 s34, s34, s41
	s_lshr_b32 s9, s9, 5
	s_lshl_b32 s9, s9, 2
	s_add_u32 s9, s9, s40
	s_mul_i32 s35, s9, 0x2c0000
	s_lshl_b32 s34, s34, 7
	s_add_u32 s35, s35, s34
	s_add_u32 s10, s22, s35
	s_addc_u32 s11, s23, 0
	global_load_dwordx4 v[32:35], v171, s[10:11]
	global_load_dwordx4 v[36:39], v172, s[10:11]
	global_load_dwordx4 v[40:43], v173, s[10:11]
	global_load_dwordx4 v[44:47], v174, s[10:11]
	global_load_dwordx4 v[48:51], v175, s[10:11]
	global_load_dwordx4 v[52:55], v177, s[10:11]
	global_load_dwordx4 v[56:59], v182, s[10:11]
	global_load_dwordx4 v[60:63], v183, s[10:11]
	s_lshl_b32 s35, s9, 8
	s_add_u32 s32, s20, s35
	s_addc_u32 s33, s21, 0
	global_load_dwordx4 v[152:155], v191, s[32:33]
	global_load_dwordx4 v[156:159], v191, s[32:33] offset:16
	s_waitcnt vmcnt(20)
	s_branch .Ltr_pr2_p3up

; #define LAS __attribute__((address_space(3)))
; __device__ __forceinline__ unsigned cvtpk(float lo, float hi) { f32x2_t v = {lo, hi}; bf16x2_t b = __builtin_convertvector(v, bf16x2_t); return __builtin_bit_cast(unsigned, b); }
; template <int MODE>
; __device__ __forceinline__ void transpose_item(const float* W, int N, bf16_t* WT, int ldt, int coff, LAS float* scr, int item, int lane, const float* g) {
;     ...
;     for (int i = 0; i < 32; ++i) { const int kk = 2 * i + (lane >> 5); float v = W[(size_t)(k0 + kk) * N + n0 + (lane & 31)]; if (MODE >= 1) v *= g[k0 + kk]; scr[kk * 33 + (lane & 31)] = v; }
;     asm volatile("s_waitcnt lgkmcnt(0)" ::: "memory");
;     const int c = lane & 7;
; #pragma unroll
;     for (int j = 0; j < 4; ++j) {
;         const int n = (lane >> 3) + 8 * j; const LAS float* s = scr + (8 * c) * 33 + n;
;         u32x4 o; o.x = cvtpk(s[0 * 33], s[1 * 33]); o.y = cvtpk(s[2 * 33], s[3 * 33]); o.z = cvtpk(s[4 * 33], s[5 * 33]); o.w = cvtpk(s[6 * 33], s[7 * 33]);
;         int dr = n0 + n;
;         if (MODE == 1) { dr = (dr < DFF) ? 256 * (dr >> 7) + (dr & 127) : 256 * ((dr - DFF) >> 7) + 128 + ((dr - DFF) & 127); }
;         if (MODE == 2) {
;             if (dr >= 6144) { const int t = dr - 6144, ch = t & 2047; dr = 6144 + 256 * (ch >> 7) + ((t >> 11) << 7) + (ch & 127); }
;             else if (dr >= 4096) { const int t = dr - 4096, ch = t & 1023; dr = 4096 + 256 * (ch >> 7) + ((t >> 10) << 7) + (ch & 127); }
;         }
;         *(u32x4*)(WT + (size_t)dr * ldt + coff + k0 + 8 * c) = o;
.Ltr_pr2_p3up:
	s_add_u32 s6, s6, 0x400
	s_lshr_b32 s34, s7, 7
	s_mul_hi_u32 s40, s34, 0xba2e8ba3
	s_lshr_b32 s40, s40, 3
	s_mul_i32 s41, s40, 11
	s_sub_u32 s34, s34, s41
	s_and_b32 s9, s7, 127
	s_and_b32 s41, s9, 31
	s_mul_i32 s41, s41, 11
	s_add_u32 s34, s34, s41
	s_lshr_b32 s9, s9, 5
	s_lshl_b32 s9, s9, 2
	s_add_u32 s9, s9, s40
	s_cmp_ge_u32 s34, 0xb0
	s_cselect_b32 s35, 0xb0, 0
	s_cselect_b32 s36, 0x80, 0
	s_sub_u32 s34, s34, s35
	s_lshl_b32 s34, s34, 5
	s_and_b32 s35, s34, 0xffffff80
	s_and_b32 s34, s34, 0x7f
	s_lshl_b32 s35, s35, 1
	s_add_u32 s35, s35, s34
	s_add_u32 s35, s35, s36
	s_mul_i32 s35, s35, 0x1000
	s_lshl_b32 s9, s9, 7
	s_add_u32 s35, s35, s9
	s_add_u32 s14, s44, s35
	s_addc_u32 s15, s45, 0
	ds_write_b32 v189, v64 offset:0
	ds_write_b32 v189, v65 offset:4
	ds_write_b32 v189, v66 offset:8
	ds_write_b32 v189, v67 offset:12
	ds_write_b32 v189, v68 offset:1056
	ds_write_b32 v189, v69 offset:1060
	ds_write_b32 v189, v70 offset:1064
	ds_write_b32 v189, v71 offset:1068
	ds_write_b32 v189, v72 offset:2112
	ds_write_b32 v189, v73 offset:2116
	ds_write_b32 v189, v74 offset:2120
	ds_write_b32 v189, v75 offset:2124
	ds_write_b32 v189, v76 offset:3168
	ds_write_b32 v189, v77 offset:3172
	ds_write_b32 v189, v78 offset:3176
	ds_write_b32 v189, v79 offset:3180
	ds_write_b32 v189, v80 offset:4224
	ds_write_b32 v189, v81 offset:4228
	ds_write_b32 v189, v82 offset:4232
	ds_write_b32 v189, v83 offset:4236
	ds_write_b32 v189, v84 offset:5280
	ds_write_b32 v189, v85 offset:5284
	ds_write_b32 v189, v86 offset:5288
	ds_write_b32 v189, v87 offset:5292
	ds_write_b32 v189, v88 offset:6336
	ds_write_b32 v189, v89 offset:6340
	ds_write_b32 v189, v90 offset:6344
	ds_write_b32 v189, v91 offset:6348
	ds_write_b32 v189, v92 offset:7392
	ds_write_b32 v189, v93 offset:7396
	ds_write_b32 v189, v94 offset:7400
	ds_write_b32 v189, v95 offset:7404
	s_waitcnt lgkmcnt(0)
	ds_read2_b32 v[96:97], v190 offset0:0 offset1:8
	ds_read2_b32 v[100:101], v190 offset0:33 offset1:41
	ds_read2_b32 v[104:105], v190 offset0:66 offset1:74
	ds_read2_b32 v[108:109], v190 offset0:99 offset1:107
	ds_read2_b32 v[112:113], v190 offset0:132 offset1:140
	ds_read2_b32 v[116:117], v190 offset0:165 offset1:173
	ds_read2_b32 v[120:121], v190 offset0:198 offset1:206
	ds_read2_b32 v[124:125], v190 offset0:231 offset1:239
	ds_read2_b32 v[98:99], v190 offset0:16 offset1:24
	ds_read2_b32 v[102:103], v190 offset0:49 offset1:57
	ds_read2_b32 v[106:107], v190 offset0:82 offset1:90
	ds_read2_b32 v[110:111], v190 offset0:115 offset1:123
	ds_read2_b32 v[114:115], v190 offset0:148 offset1:156
	ds_read2_b32 v[118:119], v190 offset0:181 offset1:189
	ds_read2_b32 v[122:123], v190 offset0:214 offset1:222
	ds_read2_b32 v[126:127], v190 offset0:247 offset1:255
	s_waitcnt lgkmcnt(0)
	v_mul_f32_e32 v96, v160, v96
	v_mul_f32_e32 v97, v160, v97
	v_mul_f32_e32 v98, v160, v98
	v_mul_f32_e32 v99, v160, v99
	v_mul_f32_e32 v100, v161, v100
	v_mul_f32_e32 v101, v161, v101
	v_mul_f32_e32 v102, v161, v102
	v_mul_f32_e32 v103, v161, v103
	v_mul_f32_e32 v104, v162, v104
	v_mul_f32_e32 v105, v162, v105
	v_mul_f32_e32 v106, v162, v106
	v_mul_f32_e32 v107, v162, v107
	v_mul_f32_e32 v108, v163, v108
	v_mul_f32_e32 v109, v163, v109
	v_mul_f32_e32 v110, v163, v110
	v_mul_f32_e32 v111, v163, v111
	v_mul_f32_e32 v112, v164, v112
	v_mul_f32_e32 v113, v164, v113
	v_mul_f32_e32 v114, v164, v114
	v_mul_f32_e32 v115, v164, v115
	v_mul_f32_e32 v116, v165, v116
	v_mul_f32_e32 v117, v165, v117
	v_mul_f32_e32 v118, v165, v118
	v_mul_f32_e32 v119, v165, v119
	v_mul_f32_e32 v120, v166, v120
	v_mul_f32_e32 v121, v166, v121
	v_mul_f32_e32 v122, v166, v122
	v_mul_f32_e32 v123, v166, v123
	v_mul_f32_e32 v124, v167, v124
	v_mul_f32_e32 v125, v167, v125
	v_mul_f32_e32 v126, v167, v126
	v_mul_f32_e32 v127, v167, v127
	v_cvt_pk_bf16_f32 v128, v96, v100
	v_cvt_pk_bf16_f32 v129, v104, v108
	v_cvt_pk_bf16_f32 v130, v112, v116
	v_cvt_pk_bf16_f32 v131, v120, v124
	global_store_dwordx4 v184, v[128:131], s[14:15]
	v_cvt_pk_bf16_f32 v132, v97, v101
	v_cvt_pk_bf16_f32 v133, v105, v109
	v_cvt_pk_bf16_f32 v134, v113, v117
	v_cvt_pk_bf16_f32 v135, v121, v125
	global_store_dwordx4 v185, v[132:135], s[14:15]
	v_cvt_pk_bf16_f32 v136, v98, v102
	v_cvt_pk_bf16_f32 v137, v106, v110
	v_cvt_pk_bf16_f32 v138, v114, v118
	v_cvt_pk_bf16_f32 v139, v122, v126
	global_store_dwordx4 v186, v[136:139], s[14:15]
	v_cvt_pk_bf16_f32 v140, v99, v103
	v_cvt_pk_bf16_f32 v141, v107, v111
	v_cvt_pk_bf16_f32 v142, v115, v119
	v_cvt_pk_bf16_f32 v143, v123, v127
	global_store_dwordx4 v188, v[140:143], s[14:15]
	s_add_u32 s7, s7, 0x400
	s_cmp_lt_u32 s7, 0x1600
	s_cbranch_scc0 .Ltr_done_p3up
	s_branch .Ltr_st0_p3up

; template <int MODE>
; __device__ __forceinline__ void transpose_item(const float* W, int N, bf16_t* WT, int ldt, int coff, LAS float* scr, int item, int lane, const float* g) {
;     const int nblk = N / 32, kb = item / nblk, nb = item % nblk, k0 = 64 * kb, n0 = 32 * nb;
; #pragma unroll 8
;     for (int i = 0; i < 32; ++i) { const int kk = 2 * i + (lane >> 5); float v = W[(size_t)(k0 + kk) * N + n0 + (lane & 31)]; if (MODE >= 1) v *= g[k0 + kk]; scr[kk * 33 + (lane & 31)] = v; }
; __global__ void __launch_bounds__(512, 2) mk_fwd(Args a) {
;     ...
;     if (IN(4)) {
;         pg8::Gemm g{MERGED, WO, DM, DM, DM}; pg8::StaticOrder S; S.init(MTOT / 256, DM / 256, G, bx, QLIM);
.LBB0_767:
	s_cmp_lt_i32 s70, 5
	s_cselect_b64 s[4:5], -1, 0
	s_add_u32 s22, s68, 0x10000
	s_addc_u32 s23, s69, 0
	s_and_b64 s[4:5], s[4:5], s[0:1]
	s_andn2_b64 vcc, exec, s[4:5]
	s_cbranch_vccnz .LBB0_830
	s_cmp_eq_u32 s3, 0x100
	s_cbranch_scc0 .Lp4t_done
	s_cmp_ge_u32 s2, 0x80
	s_cbranch_scc0 .Lp4t_done
	v_readlane_b32 s0, v250, 0
	v_readlane_b32 s1, v250, 1
	s_nop 3
	s_sub_u32 s0, s0, 0xd0
	s_subb_u32 s1, s1, 0
	s_load_dwordx2 s[6:7], s[0:1], 0x90
	s_load_dwordx2 s[8:9], s[0:1], 0x98
	s_add_u32 s10, s68, 0x1af00000
	s_addc_u32 s11, s69, 0
	s_lshl_b32 s14, s2, 3
	v_readfirstlane_b32 s15, v179
	s_nop 3
	s_lshr_b32 s15, s15, 6
	s_add_u32 s14, s14, s15
	s_sub_u32 s14, s14, 0x400
	s_lshl_b32 s15, s15, 14
	s_lshr_b32 s14, s15, 14
	s_lshl_b32 s14, s14, 7
	s_add_u32 s14, s14, s2
	s_sub_u32 s14, s14, 0x80
	s_waitcnt lgkmcnt(0)
	s_cmp_lt_u32 s14, 0x1600
	s_cbranch_scc0 .Ltr_done_p4up
	v_lshrrev_b32_e32 v168, 3, v220
	v_and_b32_e32 v169, 7, v220
	v_mul_u32_u24_e32 v170, 0xb000, v168
	v_lshl_add_u32 v171, v169, 4, v170
	v_add_u32_e32 v172, 0x58000, v171
	v_add_u32_e32 v173, 0xb0000, v171
	v_add_u32_e32 v174, 0x108000, v171
	v_add_u32_e32 v175, 0x160000, v171
	v_add_u32_e32 v177, 0x1b8000, v171
	v_add_u32_e32 v180, 0x210000, v171
	v_add_u32_e32 v181, 0x268000, v171
	v_mul_u32_u24_e32 v170, 0x84, v168
	v_lshl_add_u32 v170, v169, 4, v170
	v_add_u32_e32 v186, s15, v170
	v_mul_u32_u24_e32 v170, 0x420, v169
	v_lshl_add_u32 v170, v168, 2, v170
	v_add_u32_e32 v187, s15, v170
	v_mul_u32_u24_e32 v170, 0x1000, v168
	v_lshl_add_u32 v182, v169, 4, v170
	v_add_u32_e32 v183, 0x8000, v182
	v_add_u32_e32 v184, 0x10000, v182
	v_add_u32_e32 v185, 0x18000, v182
	v_lshlrev_b32_e32 v188, 5, v169
	s_mov_b32 s21, s14
	s_mov_b32 s20, s14
	s_lshr_b32 s37, s20, 7
	s_mul_hi_u32 s42, s37, 0xba2e8ba3
	s_lshr_b32 s42, s42, 3
	s_mul_i32 s43, s42, 11
	s_sub_u32 s37, s37, s43
	s_and_b32 s36, s20, 127
	s_and_b32 s43, s36, 31
	s_mul_i32 s43, s43, 11
	s_add_u32 s37, s37, s43
	s_lshr_b32 s36, s36, 5
	s_lshl_b32 s36, s36, 2
	s_add_u32 s36, s36, s42
	s_add_u32 s36, s36, 16
	s_mul_i32 s40, s36, 0x2c0000
	s_lshl_b32 s37, s37, 7
	s_add_u32 s40, s40, s37
	s_add_u32 s26, s8, s40
	s_addc_u32 s27, s9, 0
	global_load_dwordx4 v[0:3], v171, s[26:27]
	global_load_dwordx4 v[4:7], v172, s[26:27]
	global_load_dwordx4 v[8:11], v173, s[26:27]
	global_load_dwordx4 v[12:15], v174, s[26:27]
	global_load_dwordx4 v[16:19], v175, s[26:27]
	global_load_dwordx4 v[20:23], v177, s[26:27]
	global_load_dwordx4 v[24:27], v180, s[26:27]
	global_load_dwordx4 v[28:31], v181, s[26:27]
	s_lshl_b32 s40, s36, 8
	s_add_u32 s34, s6, s40
	s_addc_u32 s35, s7, 0
	global_load_dwordx4 v[144:147], v188, s[34:35]
	global_load_dwordx4 v[148:151], v188, s[34:35] offset:16
	s_add_u32 s20, s20, 0x400
	s_cmp_lt_u32 s20, 0x1600
	s_cbranch_scc0 .Ltr_p1_p4up
	s_lshr_b32 s37, s20, 7
	s_mul_hi_u32 s42, s37, 0xba2e8ba3
	s_lshr_b32 s42, s42, 3
	s_mul_i32 s43, s42, 11
	s_sub_u32 s37, s37, s43
	s_and_b32 s36, s20, 127
	s_and_b32 s43, s36, 31
	s_mul_i32 s43, s43, 11
	s_add_u32 s37, s37, s43
	s_lshr_b32 s36, s36, 5
	s_lshl_b32 s36, s36, 2
	s_add_u32 s36, s36, s42
	s_add_u32 s36, s36, 16
	s_mul_i32 s40, s36, 0x2c0000
	s_lshl_b32 s37, s37, 7
	s_add_u32 s40, s40, s37
	s_add_u32 s26, s8, s40
	s_addc_u32 s27, s9, 0
	global_load_dwordx4 v[32:35], v171, s[26:27]
	global_load_dwordx4 v[36:39], v172, s[26:27]
	global_load_dwordx4 v[40:43], v173, s[26:27]
	global_load_dwordx4 v[44:47], v174, s[26:27]
	global_load_dwordx4 v[48:51], v175, s[26:27]
	global_load_dwordx4 v[52:55], v177, s[26:27]
	global_load_dwordx4 v[56:59], v180, s[26:27]
	global_load_dwordx4 v[60:63], v181, s[26:27]
	s_lshl_b32 s40, s36, 8
	s_add_u32 s34, s6, s40
	s_addc_u32 s35, s7, 0
	global_load_dwordx4 v[152:155], v188, s[34:35]
	global_load_dwordx4 v[156:159], v188, s[34:35] offset:16

; template <int MODE>
; __device__ __forceinline__ void transpose_item(const float* W, int N, bf16_t* WT, int ldt, int coff, LAS float* scr, int item, int lane, const float* g) {
;     const int nblk = N / 32, kb = item / nblk, nb = item % nblk, k0 = 64 * kb, n0 = 32 * nb;
; #pragma unroll 8
;     for (int i = 0; i < 32; ++i) { const int kk = 2 * i + (lane >> 5); float v = W[(size_t)(k0 + kk) * N + n0 + (lane & 31)]; if (MODE >= 1) v *= g[k0 + kk]; scr[kk * 33 + (lane & 31)] = v; }
.Ltr_st0_p4up:
	s_cmp_lt_u32 s20, 0x1600
	s_cbranch_scc0 .Ltr_nl0_p4up
	s_lshr_b32 s37, s20, 7
	s_mul_hi_u32 s42, s37, 0xba2e8ba3
	s_lshr_b32 s42, s42, 3
	s_mul_i32 s43, s42, 11
	s_sub_u32 s37, s37, s43
	s_and_b32 s36, s20, 127
	s_and_b32 s43, s36, 31
	s_mul_i32 s43, s43, 11
	s_add_u32 s37, s37, s43
	s_lshr_b32 s36, s36, 5
	s_lshl_b32 s36, s36, 2
	s_add_u32 s36, s36, s42
	s_add_u32 s36, s36, 16
	s_mul_i32 s40, s36, 0x2c0000
	s_lshl_b32 s37, s37, 7
	s_add_u32 s40, s40, s37
	s_add_u32 s26, s8, s40
	s_addc_u32 s27, s9, 0
	global_load_dwordx4 v[64:67], v171, s[26:27]
	global_load_dwordx4 v[68:71], v172, s[26:27]
	global_load_dwordx4 v[72:75], v173, s[26:27]
	global_load_dwordx4 v[76:79], v174, s[26:27]
	global_load_dwordx4 v[80:83], v175, s[26:27]
	global_load_dwordx4 v[84:87], v177, s[26:27]
	global_load_dwordx4 v[88:91], v180, s[26:27]
	global_load_dwordx4 v[92:95], v181, s[26:27]
	s_lshl_b32 s40, s36, 8
	s_add_u32 s34, s6, s40
	s_addc_u32 s35, s7, 0
	global_load_dwordx4 v[160:163], v188, s[34:35]
	global_load_dwordx4 v[164:167], v188, s[34:35] offset:16
	s_waitcnt vmcnt(20)
	s_branch .Ltr_pr0_p4up
.Ltr_nl0_p4up:
	s_sub_u32 s36, s20, 0x400
	s_cmp_lt_u32 s36, 0x1600
	s_cbranch_scc0 .Ltr_w00_p4up
	s_waitcnt vmcnt(10)
	s_branch .Ltr_pr0_p4up

; #define LAS __attribute__((address_space(3)))
; __device__ __forceinline__ unsigned cvtpk(float lo, float hi) { f32x2_t v = {lo, hi}; bf16x2_t b = __builtin_convertvector(v, bf16x2_t); return __builtin_bit_cast(unsigned, b); }
; template <int MODE>
; __device__ __forceinline__ void transpose_item(const float* W, int N, bf16_t* WT, int ldt, int coff, LAS float* scr, int item, int lane, const float* g) {
;     const int nblk = N / 32, kb = item / nblk, nb = item % nblk, k0 = 64 * kb, n0 = 32 * nb;
; #pragma unroll 8
;     for (int i = 0; i < 32; ++i) { const int kk = 2 * i + (lane >> 5); float v = W[(size_t)(k0 + kk) * N + n0 + (lane & 31)]; if (MODE >= 1) v *= g[k0 + kk]; scr[kk * 33 + (lane & 31)] = v; }
;     asm volatile("s_waitcnt lgkmcnt(0)" ::: "memory");
;     const int c = lane & 7;
; #pragma unroll
;     for (int j = 0; j < 4; ++j) {
;         const int n = (lane >> 3) + 8 * j; const LAS float* s = scr + (8 * c) * 33 + n;
;         u32x4 o; o.x = cvtpk(s[0 * 33], s[1 * 33]); o.y = cvtpk(s[2 * 33], s[3 * 33]); o.z = cvtpk(s[4 * 33], s[5 * 33]); o.w = cvtpk(s[6 * 33], s[7 * 33]);
;         int dr = n0 + n;
;         if (MODE == 1) { dr = (dr < DFF) ? 256 * (dr >> 7) + (dr & 127) : 256 * ((dr - DFF) >> 7) + 128 + ((dr - DFF) & 127); }
;         if (MODE == 2) {
;             if (dr >= 6144) { const int t = dr - 6144, ch = t & 2047; dr = 6144 + 256 * (ch >> 7) + ((t >> 11) << 7) + (ch & 127); }
;             else if (dr >= 4096) { const int t = dr - 4096, ch = t & 1023; dr = 4096 + 256 * (ch >> 7) + ((t >> 10) << 7) + (ch & 127); }
;         }
;         *(u32x4*)(WT + (size_t)dr * ldt + coff + k0 + 8 * c) = o;
.Ltr_pr0_p4up:
	s_add_u32 s20, s20, 0x400
	s_lshr_b32 s37, s21, 7
	s_mul_hi_u32 s42, s37, 0xba2e8ba3
	s_lshr_b32 s42, s42, 3
	s_mul_i32 s43, s42, 11
	s_sub_u32 s37, s37, s43
	s_and_b32 s36, s21, 127
	s_and_b32 s43, s36, 31
	s_mul_i32 s43, s43, 11
	s_add_u32 s37, s37, s43
	s_lshr_b32 s36, s36, 5
	s_lshl_b32 s36, s36, 2
	s_add_u32 s36, s36, s42
	s_add_u32 s36, s36, 16
	s_cmp_ge_u32 s37, 0xb0
	s_cselect_b32 s40, 0xb0, 0
	s_cselect_b32 s41, 0x80, 0
	s_sub_u32 s37, s37, s40
	s_lshl_b32 s37, s37, 5
	s_and_b32 s40, s37, 0xffffff80
	s_and_b32 s37, s37, 0x7f
	s_lshl_b32 s40, s40, 1
	s_add_u32 s40, s40, s37
	s_add_u32 s40, s40, s41
	s_mul_i32 s40, s40, 0x1000
	s_lshl_b32 s36, s36, 7
	s_add_u32 s40, s40, s36
	s_add_u32 s32, s10, s40
	s_addc_u32 s33, s11, 0
	ds_write_b32 v186, v0 offset:0
	ds_write_b32 v186, v1 offset:4
	ds_write_b32 v186, v2 offset:8
	ds_write_b32 v186, v3 offset:12
	ds_write_b32 v186, v4 offset:1056
	ds_write_b32 v186, v5 offset:1060
	ds_write_b32 v186, v6 offset:1064
	ds_write_b32 v186, v7 offset:1068
	ds_write_b32 v186, v8 offset:2112
	ds_write_b32 v186, v9 offset:2116
	ds_write_b32 v186, v10 offset:2120
	ds_write_b32 v186, v11 offset:2124
	ds_write_b32 v186, v12 offset:3168
	ds_write_b32 v186, v13 offset:3172
	ds_write_b32 v186, v14 offset:3176
	ds_write_b32 v186, v15 offset:3180
	ds_write_b32 v186, v16 offset:4224
	ds_write_b32 v186, v17 offset:4228
	ds_write_b32 v186, v18 offset:4232
	ds_write_b32 v186, v19 offset:4236
	ds_write_b32 v186, v20 offset:5280
	ds_write_b32 v186, v21 offset:5284
	ds_write_b32 v186, v22 offset:5288
	ds_write_b32 v186, v23 offset:5292
	ds_write_b32 v186, v24 offset:6336
	ds_write_b32 v186, v25 offset:6340
	ds_write_b32 v186, v26 offset:6344
	ds_write_b32 v186, v27 offset:6348
	ds_write_b32 v186, v28 offset:7392
	ds_write_b32 v186, v29 offset:7396
	ds_write_b32 v186, v30 offset:7400
	ds_write_b32 v186, v31 offset:7404
	s_waitcnt lgkmcnt(0)
	ds_read2_b32 v[96:97], v187 offset0:0 offset1:8
	ds_read2_b32 v[100:101], v187 offset0:33 offset1:41
	ds_read2_b32 v[104:105], v187 offset0:66 offset1:74
	ds_read2_b32 v[108:109], v187 offset0:99 offset1:107
	ds_read2_b32 v[112:113], v187 offset0:132 offset1:140
	ds_read2_b32 v[116:117], v187 offset0:165 offset1:173
	ds_read2_b32 v[120:121], v187 offset0:198 offset1:206
	ds_read2_b32 v[124:125], v187 offset0:231 offset1:239
	ds_read2_b32 v[98:99], v187 offset0:16 offset1:24
	ds_read2_b32 v[102:103], v187 offset0:49 offset1:57
	ds_read2_b32 v[106:107], v187 offset0:82 offset1:90
	ds_read2_b32 v[110:111], v187 offset0:115 offset1:123
	ds_read2_b32 v[114:115], v187 offset0:148 offset1:156
	ds_read2_b32 v[118:119], v187 offset0:181 offset1:189
	ds_read2_b32 v[122:123], v187 offset0:214 offset1:222
	ds_read2_b32 v[126:127], v187 offset0:247 offset1:255
	s_waitcnt lgkmcnt(0)
	v_mul_f32_e32 v96, v144, v96
	v_mul_f32_e32 v97, v144, v97
	v_mul_f32_e32 v98, v144, v98
	v_mul_f32_e32 v99, v144, v99
	v_mul_f32_e32 v100, v145, v100
	v_mul_f32_e32 v101, v145, v101
	v_mul_f32_e32 v102, v145, v102
	v_mul_f32_e32 v103, v145, v103
	v_mul_f32_e32 v104, v146, v104
	v_mul_f32_e32 v105, v146, v105
	v_mul_f32_e32 v106, v146, v106
	v_mul_f32_e32 v107, v146, v107
	v_mul_f32_e32 v108, v147, v108
	v_mul_f32_e32 v109, v147, v109
	v_mul_f32_e32 v110, v147, v110
	v_mul_f32_e32 v111, v147, v111
	v_mul_f32_e32 v112, v148, v112
	v_mul_f32_e32 v113, v148, v113
	v_mul_f32_e32 v114, v148, v114
	v_mul_f32_e32 v115, v148, v115
	v_mul_f32_e32 v116, v149, v116
	v_mul_f32_e32 v117, v149, v117
	v_mul_f32_e32 v118, v149, v118
	v_mul_f32_e32 v119, v149, v119
	v_mul_f32_e32 v120, v150, v120
	v_mul_f32_e32 v121, v150, v121
	v_mul_f32_e32 v122, v150, v122
	v_mul_f32_e32 v123, v150, v123
	v_mul_f32_e32 v124, v151, v124
	v_mul_f32_e32 v125, v151, v125
	v_mul_f32_e32 v126, v151, v126
	v_mul_f32_e32 v127, v151, v127
	v_cvt_pk_bf16_f32 v128, v96, v100
	v_cvt_pk_bf16_f32 v129, v104, v108
	v_cvt_pk_bf16_f32 v130, v112, v116
	v_cvt_pk_bf16_f32 v131, v120, v124
	global_store_dwordx4 v182, v[128:131], s[32:33]
	v_cvt_pk_bf16_f32 v132, v97, v101
	v_cvt_pk_bf16_f32 v133, v105, v109
	v_cvt_pk_bf16_f32 v134, v113, v117
	v_cvt_pk_bf16_f32 v135, v121, v125
	global_store_dwordx4 v183, v[132:135], s[32:33]
	v_cvt_pk_bf16_f32 v136, v98, v102
	v_cvt_pk_bf16_f32 v137, v106, v110
	v_cvt_pk_bf16_f32 v138, v114, v118
	v_cvt_pk_bf16_f32 v139, v122, v126
	global_store_dwordx4 v184, v[136:139], s[32:33]
	v_cvt_pk_bf16_f32 v140, v99, v103
	v_cvt_pk_bf16_f32 v141, v107, v111
	v_cvt_pk_bf16_f32 v142, v115, v119
	v_cvt_pk_bf16_f32 v143, v123, v127
	global_store_dwordx4 v185, v[140:143], s[32:33]
	s_add_u32 s21, s21, 0x400
	s_cmp_lt_u32 s21, 0x1600
	s_cbranch_scc0 .Ltr_done_p4up
.Ltr_st1_p4up:
	s_cmp_lt_u32 s20, 0x1600
	s_cbranch_scc0 .Ltr_nl1_p4up
	s_lshr_b32 s37, s20, 7
	s_mul_hi_u32 s42, s37, 0xba2e8ba3
	s_lshr_b32 s42, s42, 3
	s_mul_i32 s43, s42, 11
	s_sub_u32 s37, s37, s43
	s_and_b32 s36, s20, 127
	s_and_b32 s43, s36, 31
	s_mul_i32 s43, s43, 11
	s_add_u32 s37, s37, s43
	s_lshr_b32 s36, s36, 5
	s_lshl_b32 s36, s36, 2
	s_add_u32 s36, s36, s42
	s_add_u32 s36, s36, 16
	s_mul_i32 s40, s36, 0x2c0000
	s_lshl_b32 s37, s37, 7
	s_add_u32 s40, s40, s37
	s_add_u32 s26, s8, s40
	s_addc_u32 s27, s9, 0
	global_load_dwordx4 v[0:3], v171, s[26:27]
	global_load_dwordx4 v[4:7], v172, s[26:27]
	global_load_dwordx4 v[8:11], v173, s[26:27]
	global_load_dwordx4 v[12:15], v174, s[26:27]
	global_load_dwordx4 v[16:19], v175, s[26:27]
	global_load_dwordx4 v[20:23], v177, s[26:27]
	global_load_dwordx4 v[24:27], v180, s[26:27]
	global_load_dwordx4 v[28:31], v181, s[26:27]
	s_lshl_b32 s40, s36, 8
	s_add_u32 s34, s6, s40
	s_addc_u32 s35, s7, 0
	global_load_dwordx4 v[144:147], v188, s[34:35]
	global_load_dwordx4 v[148:151], v188, s[34:35] offset:16
	s_waitcnt vmcnt(20)
	s_branch .Ltr_pr1_p4up

; #define LAS __attribute__((address_space(3)))
; __device__ __forceinline__ unsigned cvtpk(float lo, float hi) { f32x2_t v = {lo, hi}; bf16x2_t b = __builtin_convertvector(v, bf16x2_t); return __builtin_bit_cast(unsigned, b); }
; template <int MODE>
; __device__ __forceinline__ void transpose_item(const float* W, int N, bf16_t* WT, int ldt, int coff, LAS float* scr, int item, int lane, const float* g) {
;     const int nblk = N / 32, kb = item / nblk, nb = item % nblk, k0 = 64 * kb, n0 = 32 * nb;
; #pragma unroll 8
;     for (int i = 0; i < 32; ++i) { const int kk = 2 * i + (lane >> 5); float v = W[(size_t)(k0 + kk) * N + n0 + (lane & 31)]; if (MODE >= 1) v *= g[k0 + kk]; scr[kk * 33 + (lane & 31)] = v; }
;     asm volatile("s_waitcnt lgkmcnt(0)" ::: "memory");
;     const int c = lane & 7;
; #pragma unroll
;     for (int j = 0; j < 4; ++j) {
;         const int n = (lane >> 3) + 8 * j; const LAS float* s = scr + (8 * c) * 33 + n;
;         u32x4 o; o.x = cvtpk(s[0 * 33], s[1 * 33]); o.y = cvtpk(s[2 * 33], s[3 * 33]); o.z = cvtpk(s[4 * 33], s[5 * 33]); o.w = cvtpk(s[6 * 33], s[7 * 33]);
;         int dr = n0 + n;
;         if (MODE == 1) { dr = (dr < DFF) ? 256 * (dr >> 7) + (dr & 127) : 256 * ((dr - DFF) >> 7) + 128 + ((dr - DFF) & 127); }
;         if (MODE == 2) {
;             if (dr >= 6144) { const int t = dr - 6144, ch = t & 2047; dr = 6144 + 256 * (ch >> 7) + ((t >> 11) << 7) + (ch & 127); }
;             else if (dr >= 4096) { const int t = dr - 4096, ch = t & 1023; dr = 4096 + 256 * (ch >> 7) + ((t >> 10) << 7) + (ch & 127); }
;         }
;         *(u32x4*)(WT + (size_t)dr * ldt + coff + k0 + 8 * c) = o;
.Ltr_pr1_p4up:
	s_add_u32 s20, s20, 0x400
	s_lshr_b32 s37, s21, 7
	s_mul_hi_u32 s42, s37, 0xba2e8ba3
	s_lshr_b32 s42, s42, 3
	s_mul_i32 s43, s42, 11
	s_sub_u32 s37, s37, s43
	s_and_b32 s36, s21, 127
	s_and_b32 s43, s36, 31
	s_mul_i32 s43, s43, 11
	s_add_u32 s37, s37, s43
	s_lshr_b32 s36, s36, 5
	s_lshl_b32 s36, s36, 2
	s_add_u32 s36, s36, s42
	s_add_u32 s36, s36, 16
	s_cmp_ge_u32 s37, 0xb0
	s_cselect_b32 s40, 0xb0, 0
	s_cselect_b32 s41, 0x80, 0
	s_sub_u32 s37, s37, s40
	s_lshl_b32 s37, s37, 5
	s_and_b32 s40, s37, 0xffffff80
	s_and_b32 s37, s37, 0x7f
	s_lshl_b32 s40, s40, 1
	s_add_u32 s40, s40, s37
	s_add_u32 s40, s40, s41
	s_mul_i32 s40, s40, 0x1000
	s_lshl_b32 s36, s36, 7
	s_add_u32 s40, s40, s36
	s_add_u32 s32, s10, s40
	s_addc_u32 s33, s11, 0
	ds_write_b32 v186, v32 offset:0
	ds_write_b32 v186, v33 offset:4
	ds_write_b32 v186, v34 offset:8
	ds_write_b32 v186, v35 offset:12
	ds_write_b32 v186, v36 offset:1056
	ds_write_b32 v186, v37 offset:1060
	ds_write_b32 v186, v38 offset:1064
	ds_write_b32 v186, v39 offset:1068
	ds_write_b32 v186, v40 offset:2112
	ds_write_b32 v186, v41 offset:2116
	ds_write_b32 v186, v42 offset:2120
	ds_write_b32 v186, v43 offset:2124
	ds_write_b32 v186, v44 offset:3168
	ds_write_b32 v186, v45 offset:3172
	ds_write_b32 v186, v46 offset:3176
	ds_write_b32 v186, v47 offset:3180
	ds_write_b32 v186, v48 offset:4224
	ds_write_b32 v186, v49 offset:4228
	ds_write_b32 v186, v50 offset:4232
	ds_write_b32 v186, v51 offset:4236
	ds_write_b32 v186, v52 offset:5280
	ds_write_b32 v186, v53 offset:5284
	ds_write_b32 v186, v54 offset:5288
	ds_write_b32 v186, v55 offset:5292
	ds_write_b32 v186, v56 offset:6336
	ds_write_b32 v186, v57 offset:6340
	ds_write_b32 v186, v58 offset:6344
	ds_write_b32 v186, v59 offset:6348
	ds_write_b32 v186, v60 offset:7392
	ds_write_b32 v186, v61 offset:7396
	ds_write_b32 v186, v62 offset:7400
	ds_write_b32 v186, v63 offset:7404
	s_waitcnt lgkmcnt(0)
	ds_read2_b32 v[96:97], v187 offset0:0 offset1:8
	ds_read2_b32 v[100:101], v187 offset0:33 offset1:41
	ds_read2_b32 v[104:105], v187 offset0:66 offset1:74
	ds_read2_b32 v[108:109], v187 offset0:99 offset1:107
	ds_read2_b32 v[112:113], v187 offset0:132 offset1:140
	ds_read2_b32 v[116:117], v187 offset0:165 offset1:173
	ds_read2_b32 v[120:121], v187 offset0:198 offset1:206
	ds_read2_b32 v[124:125], v187 offset0:231 offset1:239
	ds_read2_b32 v[98:99], v187 offset0:16 offset1:24
	ds_read2_b32 v[102:103], v187 offset0:49 offset1:57
	ds_read2_b32 v[106:107], v187 offset0:82 offset1:90
	ds_read2_b32 v[110:111], v187 offset0:115 offset1:123
	ds_read2_b32 v[114:115], v187 offset0:148 offset1:156
	ds_read2_b32 v[118:119], v187 offset0:181 offset1:189
	ds_read2_b32 v[122:123], v187 offset0:214 offset1:222
	ds_read2_b32 v[126:127], v187 offset0:247 offset1:255
	s_waitcnt lgkmcnt(0)
	v_mul_f32_e32 v96, v152, v96
	v_mul_f32_e32 v97, v152, v97
	v_mul_f32_e32 v98, v152, v98
	v_mul_f32_e32 v99, v152, v99
	v_mul_f32_e32 v100, v153, v100
	v_mul_f32_e32 v101, v153, v101
	v_mul_f32_e32 v102, v153, v102
	v_mul_f32_e32 v103, v153, v103
	v_mul_f32_e32 v104, v154, v104
	v_mul_f32_e32 v105, v154, v105
	v_mul_f32_e32 v106, v154, v106
	v_mul_f32_e32 v107, v154, v107
	v_mul_f32_e32 v108, v155, v108
	v_mul_f32_e32 v109, v155, v109
	v_mul_f32_e32 v110, v155, v110
	v_mul_f32_e32 v111, v155, v111
	v_mul_f32_e32 v112, v156, v112
	v_mul_f32_e32 v113, v156, v113
	v_mul_f32_e32 v114, v156, v114
	v_mul_f32_e32 v115, v156, v115
	v_mul_f32_e32 v116, v157, v116
	v_mul_f32_e32 v117, v157, v117
	v_mul_f32_e32 v118, v157, v118
	v_mul_f32_e32 v119, v157, v119
	v_mul_f32_e32 v120, v158, v120
	v_mul_f32_e32 v121, v158, v121
	v_mul_f32_e32 v122, v158, v122
	v_mul_f32_e32 v123, v158, v123
	v_mul_f32_e32 v124, v159, v124
	v_mul_f32_e32 v125, v159, v125
	v_mul_f32_e32 v126, v159, v126
	v_mul_f32_e32 v127, v159, v127
	v_cvt_pk_bf16_f32 v128, v96, v100
	v_cvt_pk_bf16_f32 v129, v104, v108
	v_cvt_pk_bf16_f32 v130, v112, v116
	v_cvt_pk_bf16_f32 v131, v120, v124
	global_store_dwordx4 v182, v[128:131], s[32:33]
	v_cvt_pk_bf16_f32 v132, v97, v101
	v_cvt_pk_bf16_f32 v133, v105, v109
	v_cvt_pk_bf16_f32 v134, v113, v117
	v_cvt_pk_bf16_f32 v135, v121, v125
	global_store_dwordx4 v183, v[132:135], s[32:33]
	v_cvt_pk_bf16_f32 v136, v98, v102
	v_cvt_pk_bf16_f32 v137, v106, v110
	v_cvt_pk_bf16_f32 v138, v114, v118
	v_cvt_pk_bf16_f32 v139, v122, v126
	global_store_dwordx4 v184, v[136:139], s[32:33]
	v_cvt_pk_bf16_f32 v140, v99, v103
	v_cvt_pk_bf16_f32 v141, v107, v111
	v_cvt_pk_bf16_f32 v142, v115, v119
	v_cvt_pk_bf16_f32 v143, v123, v127
	global_store_dwordx4 v185, v[140:143], s[32:33]
	s_add_u32 s21, s21, 0x400
	s_cmp_lt_u32 s21, 0x1600
	s_cbranch_scc0 .Ltr_done_p4up
.Ltr_st2_p4up:
	s_cmp_lt_u32 s20, 0x1600
	s_cbranch_scc0 .Ltr_nl2_p4up
	s_lshr_b32 s37, s20, 7
	s_mul_hi_u32 s42, s37, 0xba2e8ba3
	s_lshr_b32 s42, s42, 3
	s_mul_i32 s43, s42, 11
	s_sub_u32 s37, s37, s43
	s_and_b32 s36, s20, 127
	s_and_b32 s43, s36, 31
	s_mul_i32 s43, s43, 11
	s_add_u32 s37, s37, s43
	s_lshr_b32 s36, s36, 5
	s_lshl_b32 s36, s36, 2
	s_add_u32 s36, s36, s42
	s_add_u32 s36, s36, 16
	s_mul_i32 s40, s36, 0x2c0000
	s_lshl_b32 s37, s37, 7
	s_add_u32 s40, s40, s37
	s_add_u32 s26, s8, s40
	s_addc_u32 s27, s9, 0
	global_load_dwordx4 v[32:35], v171, s[26:27]
	global_load_dwordx4 v[36:39], v172, s[26:27]
	global_load_dwordx4 v[40:43], v173, s[26:27]
	global_load_dwordx4 v[44:47], v174, s[26:27]
	global_load_dwordx4 v[48:51], v175, s[26:27]
	global_load_dwordx4 v[52:55], v177, s[26:27]
	global_load_dwordx4 v[56:59], v180, s[26:27]
	global_load_dwordx4 v[60:63], v181, s[26:27]
	s_lshl_b32 s40, s36, 8
	s_add_u32 s34, s6, s40
	s_addc_u32 s35, s7, 0
	global_load_dwordx4 v[152:155], v188, s[34:35]
	global_load_dwordx4 v[156:159], v188, s[34:35] offset:16
	s_waitcnt vmcnt(20)
	s_branch .Ltr_pr2_p4up

; #define LAS __attribute__((address_space(3)))
; __device__ __forceinline__ unsigned cvtpk(float lo, float hi) { f32x2_t v = {lo, hi}; bf16x2_t b = __builtin_convertvector(v, bf16x2_t); return __builtin_bit_cast(unsigned, b); }
; template <int MODE>
; __device__ __forceinline__ void transpose_item(const float* W, int N, bf16_t* WT, int ldt, int coff, LAS float* scr, int item, int lane, const float* g) {
;     ...
;     for (int i = 0; i < 32; ++i) { const int kk = 2 * i + (lane >> 5); float v = W[(size_t)(k0 + kk) * N + n0 + (lane & 31)]; if (MODE >= 1) v *= g[k0 + kk]; scr[kk * 33 + (lane & 31)] = v; }
;     asm volatile("s_waitcnt lgkmcnt(0)" ::: "memory");
;     const int c = lane & 7;
; #pragma unroll
;     for (int j = 0; j < 4; ++j) {
;         const int n = (lane >> 3) + 8 * j; const LAS float* s = scr + (8 * c) * 33 + n;
;         u32x4 o; o.x = cvtpk(s[0 * 33], s[1 * 33]); o.y = cvtpk(s[2 * 33], s[3 * 33]); o.z = cvtpk(s[4 * 33], s[5 * 33]); o.w = cvtpk(s[6 * 33], s[7 * 33]);
;         int dr = n0 + n;
;         if (MODE == 1) { dr = (dr < DFF) ? 256 * (dr >> 7) + (dr & 127) : 256 * ((dr - DFF) >> 7) + 128 + ((dr - DFF) & 127); }
;         if (MODE == 2) {
;             if (dr >= 6144) { const int t = dr - 6144, ch = t & 2047; dr = 6144 + 256 * (ch >> 7) + ((t >> 11) << 7) + (ch & 127); }
;             else if (dr >= 4096) { const int t = dr - 4096, ch = t & 1023; dr = 4096 + 256 * (ch >> 7) + ((t >> 10) << 7) + (ch & 127); }
;         }
;         *(u32x4*)(WT + (size_t)dr * ldt + coff + k0 + 8 * c) = o;
.Ltr_pr2_p4up:
	s_add_u32 s20, s20, 0x400
	s_lshr_b32 s37, s21, 7
	s_mul_hi_u32 s42, s37, 0xba2e8ba3
	s_lshr_b32 s42, s42, 3
	s_mul_i32 s43, s42, 11
	s_sub_u32 s37, s37, s43
	s_and_b32 s36, s21, 127
	s_and_b32 s43, s36, 31
	s_mul_i32 s43, s43, 11
	s_add_u32 s37, s37, s43
	s_lshr_b32 s36, s36, 5
	s_lshl_b32 s36, s36, 2
	s_add_u32 s36, s36, s42
	s_add_u32 s36, s36, 16
	s_cmp_ge_u32 s37, 0xb0
	s_cselect_b32 s40, 0xb0, 0
	s_cselect_b32 s41, 0x80, 0
	s_sub_u32 s37, s37, s40
	s_lshl_b32 s37, s37, 5
	s_and_b32 s40, s37, 0xffffff80
	s_and_b32 s37, s37, 0x7f
	s_lshl_b32 s40, s40, 1
	s_add_u32 s40, s40, s37
	s_add_u32 s40, s40, s41
	s_mul_i32 s40, s40, 0x1000
	s_lshl_b32 s36, s36, 7
	s_add_u32 s40, s40, s36
	s_add_u32 s32, s10, s40
	s_addc_u32 s33, s11, 0
	ds_write_b32 v186, v64 offset:0
	ds_write_b32 v186, v65 offset:4
	ds_write_b32 v186, v66 offset:8
	ds_write_b32 v186, v67 offset:12
	ds_write_b32 v186, v68 offset:1056
	ds_write_b32 v186, v69 offset:1060
	ds_write_b32 v186, v70 offset:1064
	ds_write_b32 v186, v71 offset:1068
	ds_write_b32 v186, v72 offset:2112
	ds_write_b32 v186, v73 offset:2116
	ds_write_b32 v186, v74 offset:2120
	ds_write_b32 v186, v75 offset:2124
	ds_write_b32 v186, v76 offset:3168
	ds_write_b32 v186, v77 offset:3172
	ds_write_b32 v186, v78 offset:3176
	ds_write_b32 v186, v79 offset:3180
	ds_write_b32 v186, v80 offset:4224
	ds_write_b32 v186, v81 offset:4228
	ds_write_b32 v186, v82 offset:4232
	ds_write_b32 v186, v83 offset:4236
	ds_write_b32 v186, v84 offset:5280
	ds_write_b32 v186, v85 offset:5284
	ds_write_b32 v186, v86 offset:5288
	ds_write_b32 v186, v87 offset:5292
	ds_write_b32 v186, v88 offset:6336
	ds_write_b32 v186, v89 offset:6340
	ds_write_b32 v186, v90 offset:6344
	ds_write_b32 v186, v91 offset:6348
	ds_write_b32 v186, v92 offset:7392
	ds_write_b32 v186, v93 offset:7396
	ds_write_b32 v186, v94 offset:7400
	ds_write_b32 v186, v95 offset:7404
	s_waitcnt lgkmcnt(0)
	ds_read2_b32 v[96:97], v187 offset0:0 offset1:8
	ds_read2_b32 v[100:101], v187 offset0:33 offset1:41
	ds_read2_b32 v[104:105], v187 offset0:66 offset1:74
	ds_read2_b32 v[108:109], v187 offset0:99 offset1:107
	ds_read2_b32 v[112:113], v187 offset0:132 offset1:140
	ds_read2_b32 v[116:117], v187 offset0:165 offset1:173
	ds_read2_b32 v[120:121], v187 offset0:198 offset1:206
	ds_read2_b32 v[124:125], v187 offset0:231 offset1:239
	ds_read2_b32 v[98:99], v187 offset0:16 offset1:24
	ds_read2_b32 v[102:103], v187 offset0:49 offset1:57
	ds_read2_b32 v[106:107], v187 offset0:82 offset1:90
	ds_read2_b32 v[110:111], v187 offset0:115 offset1:123
	ds_read2_b32 v[114:115], v187 offset0:148 offset1:156
	ds_read2_b32 v[118:119], v187 offset0:181 offset1:189
	ds_read2_b32 v[122:123], v187 offset0:214 offset1:222
	ds_read2_b32 v[126:127], v187 offset0:247 offset1:255
	s_waitcnt lgkmcnt(0)
	v_mul_f32_e32 v96, v160, v96
	v_mul_f32_e32 v97, v160, v97
	v_mul_f32_e32 v98, v160, v98
	v_mul_f32_e32 v99, v160, v99
	v_mul_f32_e32 v100, v161, v100
	v_mul_f32_e32 v101, v161, v101
	v_mul_f32_e32 v102, v161, v102
	v_mul_f32_e32 v103, v161, v103
	v_mul_f32_e32 v104, v162, v104
	v_mul_f32_e32 v105, v162, v105
	v_mul_f32_e32 v106, v162, v106
	v_mul_f32_e32 v107, v162, v107
	v_mul_f32_e32 v108, v163, v108
	v_mul_f32_e32 v109, v163, v109
	v_mul_f32_e32 v110, v163, v110
	v_mul_f32_e32 v111, v163, v111
	v_mul_f32_e32 v112, v164, v112
	v_mul_f32_e32 v113, v164, v113
	v_mul_f32_e32 v114, v164, v114
	v_mul_f32_e32 v115, v164, v115
	v_mul_f32_e32 v116, v165, v116
	v_mul_f32_e32 v117, v165, v117
	v_mul_f32_e32 v118, v165, v118
	v_mul_f32_e32 v119, v165, v119
	v_mul_f32_e32 v120, v166, v120
	v_mul_f32_e32 v121, v166, v121
	v_mul_f32_e32 v122, v166, v122
	v_mul_f32_e32 v123, v166, v123
	v_mul_f32_e32 v124, v167, v124
	v_mul_f32_e32 v125, v167, v125
	v_mul_f32_e32 v126, v167, v126
	v_mul_f32_e32 v127, v167, v127
	v_cvt_pk_bf16_f32 v128, v96, v100
	v_cvt_pk_bf16_f32 v129, v104, v108
	v_cvt_pk_bf16_f32 v130, v112, v116
	v_cvt_pk_bf16_f32 v131, v120, v124
	global_store_dwordx4 v182, v[128:131], s[32:33]
	v_cvt_pk_bf16_f32 v132, v97, v101
	v_cvt_pk_bf16_f32 v133, v105, v109
	v_cvt_pk_bf16_f32 v134, v113, v117
	v_cvt_pk_bf16_f32 v135, v121, v125
	global_store_dwordx4 v183, v[132:135], s[32:33]
	v_cvt_pk_bf16_f32 v136, v98, v102
	v_cvt_pk_bf16_f32 v137, v106, v110
	v_cvt_pk_bf16_f32 v138, v114, v118
	v_cvt_pk_bf16_f32 v139, v122, v126
	global_store_dwordx4 v184, v[136:139], s[32:33]
	v_cvt_pk_bf16_f32 v140, v99, v103
	v_cvt_pk_bf16_f32 v141, v107, v111
	v_cvt_pk_bf16_f32 v142, v115, v119
	v_cvt_pk_bf16_f32 v143, v123, v127
	global_store_dwordx4 v185, v[140:143], s[32:33]
	s_add_u32 s21, s21, 0x400
	s_cmp_lt_u32 s21, 0x1600
	s_cbranch_scc0 .Ltr_done_p4up
	s_branch .Ltr_st0_p4up
